# S5 matrix preparation loops vectorised: 16-byte stores, 8 elements per thread-iteration
# speedup vs baseline: 1.0789x; 1.0031x over previous
; __device__ __forceinline__ unsigned cvt_pk_bf16(float lo, float hi) { unsigned r; asm volatile("v_cvt_pk_bf16_f32 %0, %1, %2" : "=v"(r) : "v"(lo), "v"(hi)); return r; }
; __device__ __forceinline__ void prep_s5_group(int wv, const Params& p, int layer, int g, bf16_t* bt1, bf16_t* bt2, LAS float* L) { LIDS
;     ...
;         const int i0 = tid * 8, d = i0 >> 8, hh = (i0 >> 4) & 15, h20 = i0 & 15; float acc8[8];
; #pragma unroll
;         for (int e = 0; e < 8; ++e) acc8[e] = 0.f;
;         for (int pp = 0; pp < 64; ++pp) { const float wr_ = cr[hh * 64 + pp] * apr[d * 64 + pp] - ci[hh * 64 + pp] * api[d * 64 + pp], wi_ = cr[hh * 64 + pp] * api[d * 64 + pp] + ci[hh * 64 + pp] * apr[d * 64 + pp];
; #pragma unroll
;             for (int e = 0; e < 8; ++e) acc8[e] += wr_ * bbr[pp * 16 + h20 + e] - wi_ * bbi[pp * 16 + h20 + e]; }
; #pragma unroll
;         for (int e = 0; e < 8; ++e) kt[i0 + e] = acc8[e]; }
;     __syncthreads();
;     for (int i = tid; i < 256 * KCAT; i += 512) { const int n = i / KCAT, k = i % KCAT, t = n >> 4, hh = n & 15; float v;
;         if (k < 256) { const int s = k >> 4, h2 = k & 15; v = (s <= t) ? kt[((t - s) * 16 + hh) * 16 + h2] : 0.f; }
;         else { const int pp = (k - 256) >> 1, ri = k & 1, d = t + 1; const float fr_ = cr[hh * 64 + pp] * apr[d * 64 + pp] - ci[hh * 64 + pp] * api[d * 64 + pp], fi_ = cr[hh * 64 + pp] * api[d * 64 + pp] + ci[hh * 64 + pp] * apr[d * 64 + pp];
;             v = ri ? -fi_ : fr_; }
;         bt2[(size_t)g * 256 * KCAT + i] = (bf16_t)(cvt_pk_bf16(v, 0.f) & 0xffffu); }
.LBB0_521:
	v_add_u32_e32 v48, s4, v14
	v_add_u32_e32 v54, s4, v13
	ds_read_b128 v[16:19], v15
	ds_read_b128 v[20:23], v15 offset:16
	ds_read_b128 v[24:27], v15 offset:4096
	ds_read_b128 v[28:31], v15 offset:4112
	ds_read_b128 v[32:35], v15 offset:64
	ds_read_b128 v[36:39], v15 offset:80
	ds_read_b128 v[40:43], v15 offset:4160
	ds_read_b128 v[44:47], v15 offset:4176
	ds_read2st64_b64 v[48:51], v48 offset1:8
	ds_read_b64 v[52:53], v54
	ds_read_b64 v[54:55], v54 offset:4352
	s_add_i32 s4, s4, 8
	v_add_u32_e32 v15, 0x80, v15
	s_waitcnt lgkmcnt(2)
	v_mov_b32_e32 v56, v48
	v_mov_b32_e32 v57, v50
	s_waitcnt lgkmcnt(1)
	v_mov_b32_e32 v58, v52
	s_waitcnt lgkmcnt(0)
	v_mov_b32_e32 v59, v54
	v_mov_b32_e32 v60, v50
	v_mov_b32_e32 v61, v48
	v_mov_b32_e32 v50, v49
	v_mov_b32_e32 v54, v53
	v_mov_b32_e32 v48, v51
	v_pk_mul_f32 v[52:53], v[56:57], v[58:59]
	v_pk_mul_f32 v[56:57], v[60:61], v[58:59]
	v_pk_mul_f32 v[50:51], v[50:51], v[54:55]
	v_pk_mul_f32 v[48:49], v[48:49], v[54:55]
	v_pk_add_f32 v[54:55], v[56:57], v[56:57] op_sel:[0,1] op_sel_hi:[0,1]
	v_pk_add_f32 v[52:53], v[52:53], v[52:53] op_sel:[0,1] op_sel_hi:[0,1] neg_lo:[0,1] neg_hi:[0,1]
	v_pk_add_f32 v[48:49], v[48:49], v[48:49] op_sel:[0,1] op_sel_hi:[0,1]
	v_pk_mul_f32 v[24:25], v[54:55], v[24:25]
	v_pk_mul_f32 v[26:27], v[54:55], v[26:27]
	v_pk_mul_f32 v[28:29], v[54:55], v[28:29]
	v_pk_mul_f32 v[30:31], v[54:55], v[30:31]
	v_pk_add_f32 v[50:51], v[50:51], v[50:51] op_sel:[0,1] op_sel_hi:[0,1] neg_lo:[0,1] neg_hi:[0,1]
	v_pk_mul_f32 v[40:41], v[48:49], v[40:41]
	v_pk_mul_f32 v[42:43], v[48:49], v[42:43]
	v_pk_mul_f32 v[44:45], v[48:49], v[44:45]
	v_pk_mul_f32 v[46:47], v[48:49], v[46:47]
	v_pk_fma_f32 v[16:17], v[16:17], v[52:53], v[24:25] neg_lo:[0,0,1] neg_hi:[0,0,1]
	v_pk_fma_f32 v[18:19], v[52:53], v[18:19], v[26:27] neg_lo:[0,0,1] neg_hi:[0,0,1]
	v_pk_fma_f32 v[20:21], v[52:53], v[20:21], v[28:29] neg_lo:[0,0,1] neg_hi:[0,0,1]
	v_pk_fma_f32 v[22:23], v[52:53], v[22:23], v[30:31] neg_lo:[0,0,1] neg_hi:[0,0,1]
	v_pk_fma_f32 v[24:25], v[32:33], v[50:51], v[40:41] neg_lo:[0,0,1] neg_hi:[0,0,1]
	v_pk_fma_f32 v[26:27], v[50:51], v[34:35], v[42:43] neg_lo:[0,0,1] neg_hi:[0,0,1]
	v_pk_fma_f32 v[28:29], v[50:51], v[36:37], v[44:45] neg_lo:[0,0,1] neg_hi:[0,0,1]
	v_pk_fma_f32 v[30:31], v[50:51], v[38:39], v[46:47] neg_lo:[0,0,1] neg_hi:[0,0,1]
	v_pk_add_f32 v[4:5], v[4:5], v[16:17]
	v_pk_add_f32 v[6:7], v[6:7], v[18:19]
	v_pk_add_f32 v[0:1], v[0:1], v[20:21]
	v_pk_add_f32 v[2:3], v[2:3], v[22:23]
	s_cmpk_eq_i32 s4, 0x100
	v_pk_add_f32 v[4:5], v[4:5], v[24:25]
	v_pk_add_f32 v[6:7], v[6:7], v[26:27]
	v_pk_add_f32 v[0:1], v[0:1], v[28:29]
	v_pk_add_f32 v[2:3], v[2:3], v[30:31]
	s_cbranch_scc0 .LBB0_521
	s_mov_b32 s4, 0x18000
	s_lshr_b32 s21, s0, 6
	s_and_b32 s22, s19, 63
	v_lshl_add_u32 v12, v12, 2, 16
	v_cmp_gt_i32_e32 vcc, s4, v8
	ds_write_b128 v12, v[4:7] offset:25088
	ds_write_b128 v12, v[0:3] offset:25104
	s_waitcnt lgkmcnt(0)
	s_barrier
	s_and_saveexec_b64 s[4:5], vcc
	s_cbranch_execz .LBB0_531
	v_lshl_add_u32 v20, s3, 6, v216
	s_mul_i32 s8, s21, 0xc00000
	s_mul_hi_u32 s9, s21, 0xc00000
	s_mul_i32 s10, s22, 0x30000
	s_add_u32 s8, s8, s10
	s_addc_u32 s9, s9, 0
	s_add_u32 s10, s70, s8
	s_addc_u32 s11, s23, s9
	s_mov_b32 s9, 0xaaaaaaab
	s_mov_b32 s8, 0
	v_mov_b32_e32 v21, v20
.Ls5_bt2:
	v_mul_hi_u32 v22, v21, s9
	v_lshrrev_b32_e32 v22, 5, v22
	v_mul_u32_u24_e32 v23, 48, v22
	v_sub_u32_e32 v23, v21, v23
	v_lshrrev_b32_e32 v24, 4, v22
	v_and_b32_e32 v25, 15, v22
	v_mul_u32_u24_e32 v26, 0x300, v22
	v_lshl_add_u32 v26, v23, 4, v26
	v_mov_b32_e32 v28, 0
	v_mov_b32_e32 v29, 0
	v_mov_b32_e32 v30, 0
	v_mov_b32_e32 v31, 0
	v_mov_b32_e32 v32, 0
	v_mov_b32_e32 v33, 0
	v_mov_b32_e32 v34, 0
	v_mov_b32_e32 v35, 0
	s_mov_b64 s[12:13], exec
	v_lshrrev_b32_e32 v27, 1, v23
	v_cmp_gt_u32_e32 vcc, 32, v23
	s_and_b64 exec, exec, vcc
	v_cmp_le_u32_e32 vcc, v27, v24
	s_and_b64 exec, exec, vcc
	s_cbranch_execz .Ls5_c
	v_sub_u32_e32 v27, v24, v27
	v_lshl_add_u32 v27, v27, 4, v25
	v_and_b32_e32 v36, 1, v23
	v_lshlrev_b32_e32 v36, 3, v36
	v_lshl_add_u32 v27, v27, 4, v36
	v_lshlrev_b32_e32 v27, 2, v27
	ds_read_b128 v[28:31], v27 offset:25104
	ds_read_b128 v[32:35], v27 offset:25120
	s_waitcnt lgkmcnt(0)
; __device__ __forceinline__ unsigned cvt_pk_bf16(float lo, float hi) { unsigned r; asm volatile("v_cvt_pk_bf16_f32 %0, %1, %2" : "=v"(r) : "v"(lo), "v"(hi)); return r; }
; __device__ __forceinline__ void prep_s5_group(int wv, const Params& p, int layer, int g, bf16_t* bt1, bf16_t* bt2, LAS float* L) { LIDS
;     ...
;     for (int i = tid; i < 256 * KCAT; i += 512) { const int n = i / KCAT, k = i % KCAT, t = n >> 4, hh = n & 15; float v;
;         if (k < 256) { const int s = k >> 4, h2 = k & 15; v = (s <= t) ? kt[((t - s) * 16 + hh) * 16 + h2] : 0.f; }
;         else { const int pp = (k - 256) >> 1, ri = k & 1, d = t + 1; const float fr_ = cr[hh * 64 + pp] * apr[d * 64 + pp] - ci[hh * 64 + pp] * api[d * 64 + pp], fi_ = cr[hh * 64 + pp] * api[d * 64 + pp] + ci[hh * 64 + pp] * apr[d * 64 + pp];
;             v = ri ? -fi_ : fr_; }
;         bt2[(size_t)g * 256 * KCAT + i] = (bf16_t)(cvt_pk_bf16(v, 0.f) & 0xffffu); }
;     for (int i = tid; i < 128 * 256; i += 512) { const int n = i >> 8, k = i & 255, pp = n >> 1, ri = n & 1, t = k >> 4, hh = k & 15, d = 15 - t;
;         const float er = apr[d * 64 + pp] * bbr[pp * 16 + hh] - api[d * 64 + pp] * bbi[pp * 16 + hh], ei = apr[d * 64 + pp] * bbi[pp * 16 + hh] + api[d * 64 + pp] * bbr[pp * 16 + hh];
;         bt1[(size_t)g * 128 * 256 + i] = (bf16_t)(cvt_pk_bf16(ri ? ei : er, 0.f) & 0xffffu); }
.Ls5_c:
	s_mov_b64 exec, s[12:13]
	v_cmp_le_u32_e32 vcc, 32, v23
	s_and_b64 exec, exec, vcc
	s_cbranch_execz .Ls5_st
	v_subrev_u32_e32 v27, 32, v23
	v_lshlrev_b32_e32 v27, 2, v27
	v_lshl_add_u32 v36, v25, 6, v27
	v_lshlrev_b32_e32 v36, 2, v36
	ds_read_b128 v[40:43], v36 offset:16912
	ds_read_b128 v[44:47], v36 offset:21008
	v_add_u32_e32 v36, 1, v24
	v_lshl_add_u32 v36, v36, 6, v27
	v_lshlrev_b32_e32 v36, 2, v36
	ds_read_b128 v[48:51], v36 offset:16
	ds_read_b128 v[52:55], v36 offset:4368
	s_waitcnt lgkmcnt(0)
	v_mul_f32_e32 v27, v40, v48
	v_mul_f32_e32 v36, v44, v52
	v_sub_f32_e32 v28, v27, v36
	v_mul_f32_e32 v27, v44, v48
	v_mul_f32_e32 v36, v40, v52
	v_add_f32_e32 v27, v27, v36
	v_xor_b32_e32 v29, 0x80000000, v27
	v_mul_f32_e32 v27, v41, v49
	v_mul_f32_e32 v36, v45, v53
	v_sub_f32_e32 v30, v27, v36
	v_mul_f32_e32 v27, v45, v49
	v_mul_f32_e32 v36, v41, v53
	v_add_f32_e32 v27, v27, v36
	v_xor_b32_e32 v31, 0x80000000, v27
	v_mul_f32_e32 v27, v42, v50
	v_mul_f32_e32 v36, v46, v54
	v_sub_f32_e32 v32, v27, v36
	v_mul_f32_e32 v27, v46, v50
	v_mul_f32_e32 v36, v42, v54
	v_add_f32_e32 v27, v27, v36
	v_xor_b32_e32 v33, 0x80000000, v27
	v_mul_f32_e32 v27, v43, v51
	v_mul_f32_e32 v36, v47, v55
	v_sub_f32_e32 v34, v27, v36
	v_mul_f32_e32 v27, v47, v51
	v_mul_f32_e32 v36, v43, v55
	v_add_f32_e32 v27, v27, v36
	v_xor_b32_e32 v35, 0x80000000, v27
.Ls5_st:
	s_mov_b64 exec, s[12:13]
	v_cvt_pk_bf16_f32 v56, v28, v29
	v_cvt_pk_bf16_f32 v57, v30, v31
	v_cvt_pk_bf16_f32 v58, v32, v33
	v_cvt_pk_bf16_f32 v59, v34, v35
	global_store_dwordx4 v26, v[56:59], s[10:11]
	v_add_u32_e32 v21, 0x200, v21
	s_add_i32 s8, s8, 1
	s_cmp_lt_u32 s8, 24
	s_cbranch_scc1 .Ls5_bt2
.LBB0_531:
	s_or_b64 exec, exec, s[4:5]
	s_mul_i32 s8, s21, 0x410000
	s_mul_hi_u32 s9, s21, 0x410000
	s_lshl_b32 s10, s22, 16
	s_add_u32 s8, s8, s10
	s_addc_u32 s9, s9, 0
	s_add_u32 s10, s58, s8
	s_addc_u32 s11, s59, s9
	s_mov_b32 s8, 0
	v_mov_b32_e32 v21, v20
.Ls5_bt1:
	v_lshrrev_b32_e32 v22, 5, v21
	v_and_b32_e32 v23, 31, v21
	v_lshlrev_b32_e32 v26, 9, v22
	v_lshl_add_u32 v26, v23, 4, v26
	v_lshrrev_b32_e32 v25, 1, v22
	v_lshrrev_b32_e32 v24, 1, v23
	v_sub_u32_e32 v24, 15, v24
	v_lshl_add_u32 v27, v24, 6, v25
	v_lshlrev_b32_e32 v27, 2, v27
	ds_read_b32 v56, v27 offset:16
	ds_read_b32 v57, v27 offset:4368
	v_and_b32_e32 v36, 1, v23
	v_lshlrev_b32_e32 v36, 3, v36
	v_lshl_add_u32 v36, v25, 4, v36
	v_lshlrev_b32_e32 v36, 2, v36
	ds_read_b128 v[40:43], v36 offset:8720
	ds_read_b128 v[44:47], v36 offset:8736
	ds_read_b128 v[48:51], v36 offset:12816
	ds_read_b128 v[52:55], v36 offset:12832
	v_and_b32_e32 v27, 1, v22
	v_cmp_eq_u32_e32 vcc, 0, v27
	s_waitcnt lgkmcnt(0)
	v_mul_f32_e32 v27, v56, v40
	v_mul_f32_e32 v36, v57, v48
	v_sub_f32_e32 v27, v27, v36
	v_mul_f32_e32 v36, v57, v40
	v_mul_f32_e32 v28, v56, v48
	v_add_f32_e32 v36, v36, v28
	v_cndmask_b32_e32 v28, v36, v27, vcc
	v_mul_f32_e32 v27, v56, v41
	v_mul_f32_e32 v36, v57, v49
	v_sub_f32_e32 v27, v27, v36
	v_mul_f32_e32 v36, v57, v41
	v_mul_f32_e32 v29, v56, v49
	v_add_f32_e32 v36, v36, v29
	v_cndmask_b32_e32 v29, v36, v27, vcc
	v_mul_f32_e32 v27, v56, v42
	v_mul_f32_e32 v36, v57, v50
	v_sub_f32_e32 v27, v27, v36
	v_mul_f32_e32 v36, v57, v42
	v_mul_f32_e32 v30, v56, v50
	v_add_f32_e32 v36, v36, v30
	v_cndmask_b32_e32 v30, v36, v27, vcc
	v_mul_f32_e32 v27, v56, v43
	v_mul_f32_e32 v36, v57, v51
	v_sub_f32_e32 v27, v27, v36
	v_mul_f32_e32 v36, v57, v43
	v_mul_f32_e32 v31, v56, v51
	v_add_f32_e32 v36, v36, v31
	v_cndmask_b32_e32 v31, v36, v27, vcc
	v_mul_f32_e32 v27, v56, v44
	v_mul_f32_e32 v36, v57, v52
	v_sub_f32_e32 v27, v27, v36
	v_mul_f32_e32 v36, v57, v44
	v_mul_f32_e32 v32, v56, v52
	v_add_f32_e32 v36, v36, v32
	v_cndmask_b32_e32 v32, v36, v27, vcc
	v_mul_f32_e32 v27, v56, v45
	v_mul_f32_e32 v36, v57, v53
	v_sub_f32_e32 v27, v27, v36
	v_mul_f32_e32 v36, v57, v45
	v_mul_f32_e32 v33, v56, v53
	v_add_f32_e32 v36, v36, v33
	v_cndmask_b32_e32 v33, v36, v27, vcc
	v_mul_f32_e32 v27, v56, v46
	v_mul_f32_e32 v36, v57, v54
	v_sub_f32_e32 v27, v27, v36
	v_mul_f32_e32 v36, v57, v46
	v_mul_f32_e32 v34, v56, v54
	v_add_f32_e32 v36, v36, v34
	v_cndmask_b32_e32 v34, v36, v27, vcc
	v_mul_f32_e32 v27, v56, v47
	v_mul_f32_e32 v36, v57, v55
	v_sub_f32_e32 v27, v27, v36
	v_mul_f32_e32 v36, v57, v47
	v_mul_f32_e32 v35, v56, v55
	v_add_f32_e32 v36, v36, v35
	v_cndmask_b32_e32 v35, v36, v27, vcc
	v_cvt_pk_bf16_f32 v56, v28, v29
	v_cvt_pk_bf16_f32 v57, v30, v31
	v_cvt_pk_bf16_f32 v58, v32, v33
	v_cvt_pk_bf16_f32 v59, v34, v35
	global_store_dwordx4 v26, v[56:59], s[10:11]
	v_add_u32_e32 v21, 0x200, v21
	s_add_i32 s8, s8, 1
	s_cmp_lt_u32 s8, 8
	s_cbranch_scc1 .Ls5_bt1
	s_branch .LBB0_503
